# P0: hipcc's bit-trick f32->bf16 rounding (bfe/add3/lshr/and_or) replaced by v_cvt_pk_bf16_f32 where the dataflow resolves (49 sites)
# baseline (speedup 1.0000x reference)
.LBB0_123:
	ds_read_b32 v72, v87
	ds_read_b32 v98, v87 offset:132
	ds_read_b32 v73, v87 offset:264
	ds_read_b32 v99, v87 offset:396
	ds_read_b32 v100, v87 offset:528
	ds_read_b32 v102, v87 offset:660
	ds_read_b32 v101, v87 offset:792
	ds_read_b32 v103, v87 offset:924
	s_waitcnt lgkmcnt(0)
	v_pk_mul_f32 v[72:73], v[70:71], v[72:73]
	v_pk_mul_f32 v[98:99], v[68:69], v[98:99]
	v_pk_mul_f32 v[100:101], v[66:67], v[100:101]
	v_pk_mul_f32 v[102:103], v[94:95], v[102:103]
	v_bfe_u32 v89, v103, 16, 1
	v_bfe_u32 v97, v102, 16, 1
	v_add3_u32 v97, v102, v97, s55
	v_add3_u32 v89, v103, v89, s55
	v_cvt_pk_bf16_f32 v99, v73, v99
	v_cvt_pk_bf16_f32 v98, v72, v98
	v_mad_u64_u32 v[72:73], s[24:25], s82, v80, 0
	v_bfe_u32 v105, v101, 16, 1
	v_mov_b32_e32 v102, v73
	v_bfe_u32 v104, v100, 16, 1
	v_add3_u32 v101, v101, v105, s55
	v_mad_u64_u32 v[102:103], s[24:25], s82, v65, v[102:103]
	v_add3_u32 v100, v100, v104, s55
	v_lshrrev_b32_e32 v101, 16, v101
	v_mov_b32_e32 v73, v102
	v_lshrrev_b32_e32 v100, 16, v100
	v_and_or_b32 v101, v89, s80, v101
	v_lshl_add_u64 v[72:73], v[72:73], 1, v[92:93]
	v_mov_b32_e32 v89, v77
	v_and_or_b32 v100, v97, s80, v100
	v_lshl_add_u64 v[72:73], v[72:73], 0, v[88:89]
	global_store_dwordx4 v[72:73], v[98:101], off
	ds_read_b32 v72, v87 offset:32
	ds_read_b32 v98, v87 offset:164
	ds_read_b32 v73, v87 offset:296
	ds_read_b32 v99, v87 offset:428
	ds_read_b32 v100, v87 offset:560
	ds_read_b32 v102, v87 offset:692
	ds_read_b32 v101, v87 offset:824
	ds_read_b32 v103, v87 offset:956
	s_waitcnt lgkmcnt(0)
	v_pk_mul_f32 v[72:73], v[70:71], v[72:73]
	v_pk_mul_f32 v[98:99], v[68:69], v[98:99]
	v_pk_mul_f32 v[100:101], v[66:67], v[100:101]
	v_pk_mul_f32 v[102:103], v[94:95], v[102:103]
	v_bfe_u32 v97, v103, 16, 1
	v_add3_u32 v97, v103, v97, s55
	v_cvt_pk_bf16_f32 v99, v73, v99
	v_cvt_pk_bf16_f32 v98, v72, v98
	v_mad_u64_u32 v[72:73], s[24:25], s82, v82, 0
	v_cvt_pk_bf16_f32 v100, v100, v102
	v_mov_b32_e32 v102, v73
	v_bfe_u32 v106, v101, 16, 1
	v_mad_u64_u32 v[102:103], s[24:25], s82, v75, v[102:103]
	v_add3_u32 v101, v101, v106, s55
	v_mov_b32_e32 v73, v102
	v_lshrrev_b32_e32 v101, 16, v101
	v_lshl_add_u64 v[72:73], v[72:73], 1, v[92:93]
	v_and_or_b32 v101, v97, s80, v101
	v_lshl_add_u64 v[72:73], v[72:73], 0, v[88:89]
	global_store_dwordx4 v[72:73], v[98:101], off
	ds_read_b32 v72, v87 offset:64
	ds_read_b32 v98, v87 offset:196
	ds_read_b32 v73, v87 offset:328
	ds_read_b32 v99, v87 offset:460
	ds_read_b32 v100, v87 offset:592
	ds_read_b32 v102, v87 offset:724
	ds_read_b32 v101, v87 offset:856
	ds_read_b32 v103, v87 offset:988
	s_waitcnt lgkmcnt(0)
	v_pk_mul_f32 v[72:73], v[70:71], v[72:73]
	v_pk_mul_f32 v[98:99], v[68:69], v[98:99]
	v_pk_mul_f32 v[100:101], v[66:67], v[100:101]
	v_pk_mul_f32 v[102:103], v[94:95], v[102:103]
	v_bfe_u32 v97, v103, 16, 1
	v_add3_u32 v97, v103, v97, s55
	v_cvt_pk_bf16_f32 v99, v73, v99
	v_cvt_pk_bf16_f32 v98, v72, v98
	v_mad_u64_u32 v[72:73], s[24:25], s82, v84, 0
	v_cvt_pk_bf16_f32 v100, v100, v102
	v_mov_b32_e32 v102, v73
	v_bfe_u32 v106, v101, 16, 1
	v_mad_u64_u32 v[102:103], s[24:25], s82, v79, v[102:103]
	v_add3_u32 v101, v101, v106, s55
	v_mov_b32_e32 v73, v102
	v_lshrrev_b32_e32 v101, 16, v101
	v_lshl_add_u64 v[72:73], v[72:73], 1, v[92:93]
	v_and_or_b32 v101, v97, s80, v101
	v_lshl_add_u64 v[72:73], v[72:73], 0, v[88:89]
	global_store_dwordx4 v[72:73], v[98:101], off
	ds_read_b32 v72, v87 offset:96
	ds_read_b32 v98, v87 offset:228
	ds_read_b32 v73, v87 offset:360
	ds_read_b32 v99, v87 offset:492
	ds_read_b32 v100, v87 offset:624
	ds_read_b32 v102, v87 offset:756
	ds_read_b32 v101, v87 offset:888
	ds_read_b32 v103, v87 offset:1020
	s_waitcnt lgkmcnt(0)
	v_pk_mul_f32 v[70:71], v[70:71], v[72:73]
	v_pk_mul_f32 v[68:69], v[68:69], v[98:99]
	v_pk_mul_f32 v[66:67], v[66:67], v[100:101]
	v_pk_mul_f32 v[72:73], v[94:95], v[102:103]
	v_bfe_u32 v97, v69, 16, 1
	v_bfe_u32 v94, v73, 16, 1
	v_bfe_u32 v95, v72, 16, 1
	v_bfe_u32 v98, v68, 16, 1
	v_add3_u32 v98, v68, v98, s55
	v_add3_u32 v97, v69, v97, s55
	v_add3_u32 v68, v72, v95, s55
	v_add3_u32 v69, v73, v94, s55
	v_bfe_u32 v72, v70, 16, 1
	v_bfe_u32 v73, v71, 16, 1
	v_bfe_u32 v94, v66, 16, 1
	v_bfe_u32 v95, v67, 16, 1
	v_add3_u32 v67, v67, v95, s55
	v_add3_u32 v66, v66, v94, s55
	v_add3_u32 v71, v71, v73, s55
	v_add3_u32 v70, v70, v72, s55
	v_lshrrev_b32_e32 v70, 16, v70
	v_lshrrev_b32_e32 v71, 16, v71
	v_lshrrev_b32_e32 v66, 16, v66
	v_lshrrev_b32_e32 v67, 16, v67
	v_and_or_b32 v69, v69, s80, v67
	v_and_or_b32 v68, v68, s80, v66
	v_and_or_b32 v67, v97, s80, v71
	v_and_or_b32 v66, v98, s80, v70
	v_mad_u64_u32 v[70:71], s[24:25], s82, v86, 0
	v_mov_b32_e32 v72, v71
	v_mad_u64_u32 v[72:73], s[24:25], s82, v81, v[72:73]
	v_mov_b32_e32 v71, v72
	v_lshl_add_u64 v[70:71], v[70:71], 1, v[92:93]
	v_lshl_add_u64 v[70:71], v[70:71], 0, v[88:89]
	global_store_dwordx4 v[70:71], v[66:69], off
	s_waitcnt lgkmcnt(0)

.LBB0_230:
	ds_read_b32 v72, v87
	ds_read_b32 v104, v87 offset:132
	ds_read_b32 v73, v87 offset:264
	ds_read_b32 v105, v87 offset:396
	ds_read_b32 v106, v87 offset:528
	ds_read_b32 v108, v87 offset:660
	ds_read_b32 v107, v87 offset:792
	ds_read_b32 v109, v87 offset:924
	s_waitcnt lgkmcnt(0)
	v_pk_mul_f32 v[72:73], v[70:71], v[72:73]
	s_waitcnt lgkmcnt(4)
	v_pk_mul_f32 v[104:105], v[68:69], v[104:105]
	s_andn2_b64 vcc, exec, s[26:27]
	s_waitcnt lgkmcnt(1)
	v_pk_mul_f32 v[106:107], v[66:67], v[106:107]
	s_waitcnt lgkmcnt(0)
	v_pk_mul_f32 v[108:109], v[94:95], v[108:109]
	v_bfe_u32 v89, v109, 16, 1
	v_add3_u32 v89, v109, v89, s55
	v_cvt_pk_bf16_f32 v105, v73, v105
	v_cvt_pk_bf16_f32 v104, v72, v104
	v_mad_u64_u32 v[72:73], s[28:29], s44, v80, 0
	v_bfe_u32 v112, v107, 16, 1
	v_cvt_pk_bf16_f32 v106, v106, v108
	v_mov_b32_e32 v108, v73
	v_add3_u32 v107, v107, v112, s55
	v_mad_u64_u32 v[108:109], s[28:29], s44, v65, v[108:109]
	v_lshrrev_b32_e32 v107, 16, v107
	v_mov_b32_e32 v73, v108
	v_and_or_b32 v107, v89, s80, v107
	v_lshl_add_u64 v[72:73], v[72:73], 1, v[90:91]
	v_mov_b32_e32 v89, v77
	v_lshl_add_u64 v[72:73], v[72:73], 0, v[88:89]
	global_store_dwordx4 v[72:73], v[104:107], off
	ds_read_b32 v72, v87 offset:32
	ds_read_b32 v104, v87 offset:164
	ds_read_b32 v73, v87 offset:296
	ds_read_b32 v105, v87 offset:428
	ds_read_b32 v106, v87 offset:560
	ds_read_b32 v108, v87 offset:692
	ds_read_b32 v107, v87 offset:824
	ds_read_b32 v109, v87 offset:956
	s_waitcnt lgkmcnt(0)
	v_pk_mul_f32 v[72:73], v[70:71], v[72:73]
	v_pk_mul_f32 v[104:105], v[68:69], v[104:105]
	v_pk_mul_f32 v[106:107], v[66:67], v[106:107]
	v_pk_mul_f32 v[108:109], v[94:95], v[108:109]
	v_cvt_pk_bf16_f32 v105, v73, v105
	v_cvt_pk_bf16_f32 v104, v72, v104
	v_mad_u64_u32 v[72:73], s[28:29], s44, v82, 0
	v_cvt_pk_bf16_f32 v106, v106, v108
	v_mov_b32_e32 v108, v73
	v_cvt_pk_bf16_f32 v107, v107, v109
	v_mad_u64_u32 v[108:109], s[28:29], s44, v75, v[108:109]
	v_mov_b32_e32 v73, v108
	v_lshl_add_u64 v[72:73], v[72:73], 1, v[90:91]
	v_lshl_add_u64 v[72:73], v[72:73], 0, v[88:89]
	global_store_dwordx4 v[72:73], v[104:107], off
	ds_read_b32 v72, v87 offset:64
	ds_read_b32 v104, v87 offset:196
	ds_read_b32 v73, v87 offset:328
	ds_read_b32 v105, v87 offset:460
	ds_read_b32 v106, v87 offset:592
	ds_read_b32 v108, v87 offset:724
	ds_read_b32 v107, v87 offset:856
	ds_read_b32 v109, v87 offset:988
	s_waitcnt lgkmcnt(0)
	v_pk_mul_f32 v[72:73], v[70:71], v[72:73]
	v_pk_mul_f32 v[104:105], v[68:69], v[104:105]
	v_pk_mul_f32 v[106:107], v[66:67], v[106:107]
	v_pk_mul_f32 v[108:109], v[94:95], v[108:109]
	v_cvt_pk_bf16_f32 v105, v73, v105
	v_cvt_pk_bf16_f32 v104, v72, v104
	v_mad_u64_u32 v[72:73], s[28:29], s44, v84, 0
	v_cvt_pk_bf16_f32 v106, v106, v108
	v_mov_b32_e32 v108, v73
	v_cvt_pk_bf16_f32 v107, v107, v109
	v_mad_u64_u32 v[108:109], s[28:29], s44, v79, v[108:109]
	v_mov_b32_e32 v73, v108
	v_lshl_add_u64 v[72:73], v[72:73], 1, v[90:91]
	v_lshl_add_u64 v[72:73], v[72:73], 0, v[88:89]
	global_store_dwordx4 v[72:73], v[104:107], off
	ds_read_b32 v72, v87 offset:96
	ds_read_b32 v104, v87 offset:228
	ds_read_b32 v73, v87 offset:360
	ds_read_b32 v105, v87 offset:492
	ds_read_b32 v106, v87 offset:624
	ds_read_b32 v108, v87 offset:756
	ds_read_b32 v107, v87 offset:888
	ds_read_b32 v109, v87 offset:1020
	s_waitcnt lgkmcnt(0)
	v_pk_mul_f32 v[70:71], v[70:71], v[72:73]
	v_pk_mul_f32 v[68:69], v[68:69], v[104:105]
	v_pk_mul_f32 v[66:67], v[66:67], v[106:107]
	v_pk_mul_f32 v[72:73], v[94:95], v[108:109]
	v_bfe_u32 v104, v69, 16, 1
	v_bfe_u32 v94, v73, 16, 1
	v_bfe_u32 v95, v72, 16, 1
	v_bfe_u32 v105, v68, 16, 1
	v_add3_u32 v105, v68, v105, s55
	v_add3_u32 v104, v69, v104, s55
	v_add3_u32 v68, v72, v95, s55
	v_add3_u32 v69, v73, v94, s55
	v_bfe_u32 v72, v70, 16, 1
	v_bfe_u32 v73, v71, 16, 1
	v_bfe_u32 v94, v66, 16, 1
	v_bfe_u32 v95, v67, 16, 1
	v_add3_u32 v67, v67, v95, s55
	v_add3_u32 v66, v66, v94, s55
	v_add3_u32 v71, v71, v73, s55
	v_add3_u32 v70, v70, v72, s55
	v_lshrrev_b32_e32 v70, 16, v70
	v_lshrrev_b32_e32 v71, 16, v71
	v_lshrrev_b32_e32 v66, 16, v66
	v_lshrrev_b32_e32 v67, 16, v67
	v_and_or_b32 v69, v69, s80, v67
	v_and_or_b32 v68, v68, s80, v66
	v_and_or_b32 v67, v104, s80, v71
	v_and_or_b32 v66, v105, s80, v70
	v_mad_u64_u32 v[70:71], s[28:29], s44, v86, 0
	v_mov_b32_e32 v72, v71
	v_mad_u64_u32 v[72:73], s[28:29], s44, v81, v[72:73]
	v_mov_b32_e32 v71, v72
	v_lshl_add_u64 v[70:71], v[70:71], 1, v[90:91]
	v_lshl_add_u64 v[70:71], v[70:71], 0, v[88:89]
	global_store_dwordx4 v[70:71], v[66:69], off
	s_waitcnt lgkmcnt(0)
	s_cbranch_vccnz .LBB0_124
	s_add_i32 s38, s45, s83
	s_cmp_gt_i32 s38, 0xa01f
	s_cbranch_scc1 .Lp0_w2z
	s_cmpk_gt_i32 s38, 0x15ff
	s_cbranch_scc0 .LBB0_244
	s_cmpk_gt_u32 s38, 0x2bff
	s_cbranch_scc0 .LBB0_245
	s_cmpk_gt_u32 s38, 0x41ff
	s_cbranch_scc0 .LBB0_246
	s_mov_b64 s[30:31], -1
	s_cmpk_gt_u32 s38, 0x521f
	s_mov_b64 s[34:35], -1
	s_cbranch_scc0 .LBB0_263
	s_cmpk_gt_u32 s38, 0x541f
	s_cbranch_scc0 .LBB0_247
	s_cmpk_gt_u32 s38, 0x561f
	s_cbranch_scc0 .LBB0_248
	s_cmpk_gt_u32 s38, 0x5e1f
	s_cbranch_scc0 .LBB0_249
	s_cmpk_gt_u32 s38, 0x741f
	s_cbranch_scc0 .LBB0_251
	s_cmpk_gt_u32 s38, 0x8a1f
	s_mov_b64 s[20:21], -1
	s_cbranch_scc0 .LBB0_242
	s_add_i32 s21, s46, s47
	s_add_i32 s21, s21, 0xffeebc00
	s_add_i32 s20, s38, 0xffff75e0
	s_and_b32 s28, s21, 0x7e0
	s_and_b32 s22, s20, 0xffffffc0
	s_mul_i32 s20, s28, 0x2c00
	s_add_u32 s26, s16, s20
	v_add_u32_e32 v2, s22, v85
	s_addc_u32 s27, s17, 0
	s_lshl_b64 s[20:21], s[22:23], 1
	v_ashrrev_i32_e32 v3, 31, v2
	v_readlane_b32 s56, v254, 40
	s_add_u32 s26, s26, s20
	v_lshlrev_b64 v[2:3], 13, v[2:3]
	v_readlane_b32 s70, v254, 54
	v_readlane_b32 s71, v254, 55
	s_addc_u32 s27, s27, s21
	s_lshl_b32 s22, s28, 2
	v_lshl_add_u64 v[2:3], s[70:71], 0, v[2:3]
	v_readlane_b32 s57, v254, 41
	v_readlane_b32 s58, v254, 42
	v_readlane_b32 s59, v254, 43
	v_readlane_b32 s60, v254, 44
	v_readlane_b32 s61, v254, 45
	v_readlane_b32 s62, v254, 46
	v_readlane_b32 s63, v254, 47
	v_readlane_b32 s64, v254, 48
	v_readlane_b32 s65, v254, 49
	v_readlane_b32 s66, v254, 50
	v_readlane_b32 s67, v254, 51
	v_readlane_b32 s68, v254, 52
	v_readlane_b32 s69, v254, 53
	v_lshl_add_u64 v[66:67], v[2:3], 0, s[22:23]
	s_mov_b64 s[20:21], 0

.LBB0_338:
	v_cvt_pk_bf16_f32 v2, v2, v3
	s_add_i32 s4, s4, s6
	v_cvt_pk_bf16_f32 v3, v4, v5
	v_lshl_add_u64 v[58:59], v[58:59], 0, s[10:11]
	s_cmpk_gt_i32 s4, 0x43ff
	v_lshl_add_u64 v[60:61], v[60:61], 0, s[8:9]
	global_store_dwordx2 v[62:63], v[2:3], off offset:3584
	s_cbranch_scc1 .LBB0_343
.LBB0_339:
	s_cmpk_gt_i32 s4, 0x3fff
	s_mov_b64 s[0:1], -1
	s_cbranch_scc0 .LBB0_341
	s_add_i32 s12, s4, 0xffffc000
	s_lshl_b64 s[0:1], s[12:13], 13
	v_lshl_add_u64 v[2:3], v[34:35], 0, s[0:1]
	global_load_dwordx4 v[30:33], v[2:3], off
	global_load_dwordx4 v[26:29], v[2:3], off offset:1024
	global_load_dwordx4 v[22:25], v[2:3], off offset:2048
	global_load_dwordx4 v[18:21], v[2:3], off offset:3072
	v_add_co_u32_e32 v62, vcc, s2, v2
	s_lshl_b64 s[14:15], s[12:13], 12
	s_nop 0
	v_addc_co_u32_e32 v63, vcc, 0, v3, vcc
	global_load_dwordx4 v[14:17], v[62:63], off
	global_load_dwordx4 v[10:13], v[62:63], off offset:1024
	global_load_dwordx4 v[2:5], v[62:63], off offset:3072
	global_load_dwordx4 v[6:9], v[62:63], off offset:2048
	global_load_dwordx4 v[74:77], v[38:39], off
	global_load_dwordx4 v[132:135], v[38:39], off offset:1024
	global_load_dwordx4 v[136:139], v[38:39], off offset:2048
	global_load_dwordx4 v[140:143], v[38:39], off offset:3072
	global_load_dwordx4 v[144:147], v[40:41], off
	global_load_dwordx4 v[148:151], v[42:43], off
	global_load_dwordx4 v[152:155], v[44:45], off
	global_load_dwordx4 v[156:159], v[46:47], off
	v_cmp_lt_i32_e32 vcc, v67, v66
	s_waitcnt vmcnt(0)
	v_mov_b32_e32 v78, v31
	v_cndmask_b32_e32 v62, v65, v67, vcc
	v_mov_b32_e32 v79, v27
	v_mov_b32_e32 v84, v33
	v_mov_b32_e32 v85, v29
	v_lshlrev_b32_e32 v73, 2, v62
	v_mov_b32_e32 v62, v30
	v_mov_b32_e32 v63, v26
	v_mov_b32_e32 v80, v32
	v_mov_b32_e32 v81, v28
	v_pk_mul_f32 v[86:87], v[24:25], v[24:25]
	v_pk_mul_f32 v[88:89], v[22:23], v[22:23]
	v_pk_mul_f32 v[78:79], v[78:79], v[78:79]
	v_pk_mul_f32 v[84:85], v[84:85], v[84:85]
	v_pk_mov_b32 v[92:93], v[88:89], v[86:87] op_sel:[1,0]
	v_mov_b32_e32 v89, v87
	v_pk_fma_f32 v[62:63], v[62:63], v[62:63], v[78:79]
	v_pk_fma_f32 v[78:79], v[80:81], v[80:81], v[84:85]
	v_mul_f32_e32 v82, v19, v19
	v_mul_f32_e32 v90, v21, v21
	v_pk_add_f32 v[80:81], v[92:93], v[88:89]
	v_pk_add_f32 v[62:63], v[62:63], v[78:79]
	v_mul_f32_e32 v99, v14, v14
	v_mul_f32_e32 v100, v15, v15
	v_mul_f32_e32 v101, v16, v16
	v_mul_f32_e32 v102, v17, v17
	v_pk_fma_f32 v[86:87], v[18:19], v[18:19], v[82:83] op_sel_hi:[1,1,0]
	v_pk_fma_f32 v[90:91], v[20:21], v[20:21], v[90:91] op_sel_hi:[1,1,0]
	v_pk_add_f32 v[78:79], v[80:81], v[80:81] op_sel:[0,1] op_sel_hi:[1,0]
	v_pk_add_f32 v[62:63], v[62:63], v[62:63] op_sel:[0,1] op_sel_hi:[1,0]
	v_pk_mul_f32 v[94:95], v[12:13], v[12:13]
	v_pk_mul_f32 v[96:97], v[10:11], v[10:11]
	v_mov_b32_e32 v87, v101
	v_mov_b32_e32 v91, v102
	v_mov_b32_e32 v79, v100
	v_mov_b32_e32 v63, v99
	v_pk_mov_b32 v[84:85], v[96:97], v[94:95] op_sel:[1,0]
	v_mov_b32_e32 v97, v95
	v_pk_add_f32 v[80:81], v[86:87], v[90:91]
	v_pk_add_f32 v[62:63], v[62:63], v[78:79]
	v_mul_f32_e32 v82, v7, v7
	v_mul_f32_e32 v98, v9, v9
	v_pk_add_f32 v[84:85], v[84:85], v[96:97]
	v_pk_add_f32 v[62:63], v[62:63], v[80:81]
	v_mul_f32_e32 v103, v2, v2
	v_mul_f32_e32 v104, v3, v3
	v_mul_f32_e32 v105, v4, v4
	v_mul_f32_e32 v106, v5, v5
	v_pk_fma_f32 v[88:89], v[6:7], v[6:7], v[82:83] op_sel_hi:[1,1,0]
	v_pk_fma_f32 v[92:93], v[8:9], v[8:9], v[98:99] op_sel_hi:[1,1,0]
	v_pk_add_f32 v[84:85], v[84:85], v[84:85] op_sel:[0,1] op_sel_hi:[1,0]
	v_pk_add_f32 v[62:63], v[62:63], v[62:63] op_sel:[0,1] op_sel_hi:[1,0]
	v_mov_b32_e32 v89, v105
	v_mov_b32_e32 v93, v106
	v_mov_b32_e32 v85, v104
	v_mov_b32_e32 v63, v103
	v_pk_add_f32 v[86:87], v[88:89], v[92:93]
	v_pk_add_f32 v[62:63], v[62:63], v[84:85]
	v_cmp_lt_i32_e32 vcc, v68, v66
	v_pk_add_f32 v[62:63], v[62:63], v[86:87]
	s_nop 0
	v_add_f32_e32 v62, v62, v63
	ds_bpermute_b32 v63, v73, v62
	v_cndmask_b32_e32 v73, v65, v68, vcc
	v_lshlrev_b32_e32 v73, 2, v73
	v_cmp_lt_i32_e32 vcc, v69, v66
	s_waitcnt lgkmcnt(0)
	v_add_f32_e32 v62, v62, v63
	ds_bpermute_b32 v63, v73, v62
	v_cndmask_b32_e32 v73, v65, v69, vcc
	v_lshlrev_b32_e32 v73, 2, v73
	v_cmp_lt_i32_e32 vcc, v70, v66
	s_waitcnt lgkmcnt(0)
	v_add_f32_e32 v62, v62, v63
	ds_bpermute_b32 v63, v73, v62
	v_cndmask_b32_e32 v73, v65, v70, vcc
	v_lshlrev_b32_e32 v73, 2, v73
	v_cmp_lt_i32_e32 vcc, v71, v66
	s_waitcnt lgkmcnt(0)
	v_add_f32_e32 v62, v62, v63
	ds_bpermute_b32 v63, v73, v62
	v_cndmask_b32_e32 v73, v65, v71, vcc
	v_lshlrev_b32_e32 v73, 2, v73
	v_cmp_lt_i32_e32 vcc, v72, v66
	s_waitcnt lgkmcnt(0)
	v_add_f32_e32 v62, v62, v63
	ds_bpermute_b32 v63, v73, v62
	v_cndmask_b32_e32 v73, v65, v72, vcc
	v_lshlrev_b32_e32 v73, 2, v73
	s_waitcnt lgkmcnt(0)
	v_add_f32_e32 v62, v62, v63
	ds_bpermute_b32 v63, v73, v62
	s_waitcnt lgkmcnt(0)
	v_add_f32_e32 v62, v62, v63
	v_fmamk_f32 v62, v62, 0x3a000000, v1
	v_mul_f32_e32 v63, 0x4f800000, v62
	v_cmp_gt_f32_e32 vcc, s3, v62
	s_nop 1
	v_cndmask_b32_e32 v62, v62, v63, vcc
	v_sqrt_f32_e32 v63, v62
	s_nop 0
	v_add_u32_e32 v73, -1, v63
	v_add_u32_e32 v78, 1, v63
	v_fma_f32 v79, -v73, v63, v62
	v_fma_f32 v80, -v78, v63, v62
	v_cmp_ge_f32_e64 s[0:1], 0, v79
	s_nop 1
	v_cndmask_b32_e64 v63, v63, v73, s[0:1]
	v_cmp_lt_f32_e64 s[0:1], 0, v80
	s_nop 1
	v_cndmask_b32_e64 v63, v63, v78, s[0:1]
	v_mul_f32_e32 v73, 0x37800000, v63
	v_cndmask_b32_e32 v63, v63, v73, vcc
	v_cmp_class_f32_e32 vcc, v62, v64
	s_nop 1
	v_cndmask_b32_e32 v73, v63, v62, vcc
	v_div_scale_f32 v78, s[0:1], v73, v73, 1.0
	v_rcp_f32_e32 v79, v78
	v_div_scale_f32 v80, vcc, 1.0, v73, 1.0
	v_lshl_add_u64 v[62:63], v[36:37], 0, s[14:15]
	v_fma_f32 v81, -v78, v79, 1.0
	v_fmac_f32_e32 v79, v81, v79
	v_mul_f32_e32 v81, v80, v79
	v_fma_f32 v82, -v78, v81, v80
	v_fmac_f32_e32 v81, v82, v79
	v_fma_f32 v78, -v78, v81, v80
	v_div_fmas_f32 v78, v78, v79, v81
	v_div_fixup_f32 v78, v78, v73, 1.0
	v_pk_mul_f32 v[30:31], v[30:31], v[78:79] op_sel_hi:[1,0]
	v_pk_mul_f32 v[32:33], v[32:33], v[78:79] op_sel_hi:[1,0]
	v_pk_mul_f32 v[30:31], v[74:75], v[30:31]
	v_pk_mul_f32 v[32:33], v[76:77], v[32:33]
	v_cvt_pk_bf16_f32 v30, v30, v31
	v_cvt_pk_bf16_f32 v31, v32, v33
	global_store_dwordx2 v[62:63], v[30:31], off
	s_nop 1
	v_mov_b32_e32 v30, v132
	v_mov_b32_e32 v31, v133
	v_mov_b32_e32 v32, v134
	v_mov_b32_e32 v33, v135
	v_pk_mul_f32 v[26:27], v[26:27], v[78:79] op_sel_hi:[1,0]
	v_pk_mul_f32 v[28:29], v[28:29], v[78:79] op_sel_hi:[1,0]
	v_pk_mul_f32 v[22:23], v[22:23], v[78:79] op_sel_hi:[1,0]
	v_pk_mul_f32 v[24:25], v[24:25], v[78:79] op_sel_hi:[1,0]
	v_pk_mul_f32 v[18:19], v[18:19], v[78:79] op_sel_hi:[1,0]
	v_pk_mul_f32 v[20:21], v[20:21], v[78:79] op_sel_hi:[1,0]
	v_pk_mul_f32 v[14:15], v[14:15], v[78:79] op_sel_hi:[1,0]
	v_pk_mul_f32 v[16:17], v[16:17], v[78:79] op_sel_hi:[1,0]
	v_pk_mul_f32 v[10:11], v[10:11], v[78:79] op_sel_hi:[1,0]
	v_pk_mul_f32 v[12:13], v[12:13], v[78:79] op_sel_hi:[1,0]
	v_pk_mul_f32 v[6:7], v[6:7], v[78:79] op_sel_hi:[1,0]
	v_pk_mul_f32 v[8:9], v[8:9], v[78:79] op_sel_hi:[1,0]
	v_pk_mul_f32 v[4:5], v[4:5], v[78:79] op_sel_hi:[1,0]
	v_pk_mul_f32 v[2:3], v[2:3], v[78:79] op_sel_hi:[1,0]
	s_mov_b64 s[0:1], 0
	v_pk_mul_f32 v[28:29], v[32:33], v[28:29]
	v_pk_mul_f32 v[26:27], v[30:31], v[26:27]
	v_cvt_pk_bf16_f32 v26, v26, v27
	v_cvt_pk_bf16_f32 v27, v28, v29
	global_store_dwordx2 v[62:63], v[26:27], off offset:512
	s_nop 1
	v_mov_b32_e32 v26, v136
	v_mov_b32_e32 v27, v137
	v_mov_b32_e32 v28, v138
	v_mov_b32_e32 v29, v139
	v_pk_mul_f32 v[24:25], v[28:29], v[24:25]
	v_pk_mul_f32 v[22:23], v[26:27], v[22:23]
	v_cvt_pk_bf16_f32 v22, v22, v23
	v_cvt_pk_bf16_f32 v23, v24, v25
	global_store_dwordx2 v[62:63], v[22:23], off offset:1024
	s_nop 1
	v_mov_b32_e32 v22, v140
	v_mov_b32_e32 v23, v141
	v_mov_b32_e32 v24, v142
	v_mov_b32_e32 v25, v143
	v_pk_mul_f32 v[20:21], v[24:25], v[20:21]
	v_pk_mul_f32 v[18:19], v[22:23], v[18:19]
	v_cvt_pk_bf16_f32 v18, v18, v19
	v_cvt_pk_bf16_f32 v19, v20, v21
	global_store_dwordx2 v[62:63], v[18:19], off offset:1536
	s_nop 1
	v_mov_b32_e32 v18, v144
	v_mov_b32_e32 v19, v145
	v_mov_b32_e32 v20, v146
	v_mov_b32_e32 v21, v147
	v_pk_mul_f32 v[16:17], v[20:21], v[16:17]
	v_pk_mul_f32 v[14:15], v[18:19], v[14:15]
	v_cvt_pk_bf16_f32 v14, v14, v15
	v_cvt_pk_bf16_f32 v15, v16, v17
	global_store_dwordx2 v[62:63], v[14:15], off offset:2048
	s_nop 1
	v_mov_b32_e32 v14, v148
	v_mov_b32_e32 v15, v149
	v_mov_b32_e32 v16, v150
	v_mov_b32_e32 v17, v151
	v_pk_mul_f32 v[12:13], v[12:13], v[16:17]
	v_pk_mul_f32 v[10:11], v[10:11], v[14:15]
	v_cvt_pk_bf16_f32 v10, v10, v11
	v_cvt_pk_bf16_f32 v11, v12, v13
	global_store_dwordx2 v[62:63], v[10:11], off offset:2560
	s_nop 1
	v_mov_b32_e32 v10, v152
	v_mov_b32_e32 v11, v153
	v_mov_b32_e32 v12, v154
	v_mov_b32_e32 v13, v155
	v_pk_mul_f32 v[8:9], v[8:9], v[12:13]
	v_pk_mul_f32 v[6:7], v[6:7], v[10:11]
	v_cvt_pk_bf16_f32 v6, v6, v7
	v_cvt_pk_bf16_f32 v7, v8, v9
	global_store_dwordx2 v[62:63], v[6:7], off offset:3072
	s_nop 1
	v_mov_b32_e32 v6, v156
	v_mov_b32_e32 v7, v157
	v_mov_b32_e32 v8, v158
	v_mov_b32_e32 v9, v159
	v_pk_mul_f32 v[2:3], v[2:3], v[6:7]
	v_pk_mul_f32 v[4:5], v[4:5], v[8:9]
.LBB0_341:
	s_andn2_b64 vcc, exec, s[0:1]
	s_cbranch_vccnz .LBB0_338
	global_load_dwordx4 v[30:33], v[58:59], off offset:-4096
	global_load_dwordx4 v[26:29], v[58:59], off offset:-3072
	global_load_dwordx4 v[22:25], v[58:59], off offset:-2048
	global_load_dwordx4 v[14:17], v[58:59], off
	global_load_dwordx4 v[18:21], v[58:59], off offset:-1024
	global_load_dwordx4 v[10:13], v[58:59], off offset:1024
	global_load_dwordx4 v[2:5], v[58:59], off offset:3072
	global_load_dwordx4 v[6:9], v[58:59], off offset:2048
	global_load_dwordx4 v[74:77], v[48:49], off
	global_load_dwordx4 v[132:135], v[48:49], off offset:1024
	global_load_dwordx4 v[136:139], v[48:49], off offset:2048
	global_load_dwordx4 v[140:143], v[48:49], off offset:3072
	global_load_dwordx4 v[144:147], v[50:51], off
	global_load_dwordx4 v[148:151], v[52:53], off
	global_load_dwordx4 v[152:155], v[54:55], off
	global_load_dwordx4 v[156:159], v[56:57], off
	v_cmp_lt_i32_e32 vcc, v67, v66
	s_waitcnt vmcnt(0)
	v_mov_b32_e32 v78, v31
	v_cndmask_b32_e32 v62, v65, v67, vcc
	v_mov_b32_e32 v79, v27
	v_mov_b32_e32 v84, v33
	v_mov_b32_e32 v85, v29
	v_lshlrev_b32_e32 v73, 2, v62
	v_mov_b32_e32 v62, v30
	v_mov_b32_e32 v63, v26
	v_mov_b32_e32 v80, v32
	v_mov_b32_e32 v81, v28
	v_pk_mul_f32 v[86:87], v[24:25], v[24:25]
	v_pk_mul_f32 v[88:89], v[22:23], v[22:23]
	v_pk_mul_f32 v[78:79], v[78:79], v[78:79]
	v_pk_mul_f32 v[84:85], v[84:85], v[84:85]
	v_pk_mov_b32 v[100:101], v[88:89], v[86:87] op_sel:[1,0]
	v_mov_b32_e32 v89, v87
	v_pk_fma_f32 v[62:63], v[62:63], v[62:63], v[78:79]
	v_pk_fma_f32 v[78:79], v[80:81], v[80:81], v[84:85]
	v_mul_f32_e32 v82, v19, v19
	v_mul_f32_e32 v90, v21, v21
	v_pk_add_f32 v[80:81], v[100:101], v[88:89]
	v_pk_add_f32 v[62:63], v[62:63], v[78:79]
	v_mul_f32_e32 v99, v14, v14
	v_mul_f32_e32 v104, v15, v15
	v_mul_f32_e32 v105, v16, v16
	v_mul_f32_e32 v106, v17, v17
	v_pk_fma_f32 v[86:87], v[18:19], v[18:19], v[82:83] op_sel_hi:[1,1,0]
	v_pk_fma_f32 v[90:91], v[20:21], v[20:21], v[90:91] op_sel_hi:[1,1,0]
	v_pk_add_f32 v[78:79], v[80:81], v[80:81] op_sel:[0,1] op_sel_hi:[1,0]
	v_pk_add_f32 v[62:63], v[62:63], v[62:63] op_sel:[0,1] op_sel_hi:[1,0]
	v_pk_mul_f32 v[92:93], v[12:13], v[12:13]
	v_pk_mul_f32 v[94:95], v[10:11], v[10:11]
	v_mov_b32_e32 v87, v105
	v_mov_b32_e32 v91, v106
	v_mov_b32_e32 v79, v104
	v_mov_b32_e32 v63, v99
	v_pk_mov_b32 v[102:103], v[94:95], v[92:93] op_sel:[1,0]
	v_mov_b32_e32 v95, v93
	v_pk_add_f32 v[80:81], v[86:87], v[90:91]
	v_pk_add_f32 v[62:63], v[62:63], v[78:79]
	v_mul_f32_e32 v96, v7, v7
	v_mul_f32_e32 v98, v9, v9
	v_pk_add_f32 v[84:85], v[102:103], v[94:95]
	v_pk_add_f32 v[62:63], v[62:63], v[80:81]
	v_mul_f32_e32 v107, v2, v2
	v_mul_f32_e32 v108, v3, v3
	v_mul_f32_e32 v109, v4, v4
	v_mul_f32_e32 v110, v5, v5
	v_pk_fma_f32 v[92:93], v[6:7], v[6:7], v[96:97] op_sel_hi:[1,1,0]
	v_pk_fma_f32 v[96:97], v[8:9], v[8:9], v[98:99] op_sel_hi:[1,1,0]
	v_pk_add_f32 v[84:85], v[84:85], v[84:85] op_sel:[0,1] op_sel_hi:[1,0]
	v_pk_add_f32 v[62:63], v[62:63], v[62:63] op_sel:[0,1] op_sel_hi:[1,0]
	v_mov_b32_e32 v93, v109
	v_mov_b32_e32 v97, v110
	v_mov_b32_e32 v85, v108
	v_mov_b32_e32 v63, v107
	v_pk_add_f32 v[86:87], v[92:93], v[96:97]
	v_pk_add_f32 v[62:63], v[62:63], v[84:85]
	v_cmp_lt_i32_e32 vcc, v68, v66
	v_pk_add_f32 v[62:63], v[62:63], v[86:87]
	s_nop 0
	v_add_f32_e32 v62, v62, v63
	ds_bpermute_b32 v63, v73, v62
	v_cndmask_b32_e32 v73, v65, v68, vcc
	v_lshlrev_b32_e32 v73, 2, v73
	v_cmp_lt_i32_e32 vcc, v69, v66
	s_waitcnt lgkmcnt(0)
	v_add_f32_e32 v62, v62, v63
	ds_bpermute_b32 v63, v73, v62
	v_cndmask_b32_e32 v73, v65, v69, vcc
	v_lshlrev_b32_e32 v73, 2, v73
	v_cmp_lt_i32_e32 vcc, v70, v66
	s_waitcnt lgkmcnt(0)
	v_add_f32_e32 v62, v62, v63
	ds_bpermute_b32 v63, v73, v62
	v_cndmask_b32_e32 v73, v65, v70, vcc
	v_lshlrev_b32_e32 v73, 2, v73
	v_cmp_lt_i32_e32 vcc, v71, v66
	s_waitcnt lgkmcnt(0)
	v_add_f32_e32 v62, v62, v63
	ds_bpermute_b32 v63, v73, v62
	v_cndmask_b32_e32 v73, v65, v71, vcc
	v_lshlrev_b32_e32 v73, 2, v73
	v_cmp_lt_i32_e32 vcc, v72, v66
	s_waitcnt lgkmcnt(0)
	v_add_f32_e32 v62, v62, v63
	ds_bpermute_b32 v63, v73, v62
	v_cndmask_b32_e32 v73, v65, v72, vcc
	v_lshlrev_b32_e32 v73, 2, v73
	s_waitcnt lgkmcnt(0)
	v_add_f32_e32 v62, v62, v63
	ds_bpermute_b32 v63, v73, v62
	s_waitcnt lgkmcnt(0)
	v_add_f32_e32 v62, v62, v63
	v_fmamk_f32 v62, v62, 0x3a000000, v1
	v_mul_f32_e32 v63, 0x4f800000, v62
	v_cmp_gt_f32_e32 vcc, s3, v62
	s_nop 1
	v_cndmask_b32_e32 v62, v62, v63, vcc
	v_sqrt_f32_e32 v63, v62
	s_nop 0
	v_add_u32_e32 v73, -1, v63
	v_add_u32_e32 v78, 1, v63
	v_fma_f32 v79, -v73, v63, v62
	v_fma_f32 v80, -v78, v63, v62
	v_cmp_ge_f32_e64 s[0:1], 0, v79
	s_nop 1
	v_cndmask_b32_e64 v63, v63, v73, s[0:1]
	v_cmp_lt_f32_e64 s[0:1], 0, v80
	s_nop 1
	v_cndmask_b32_e64 v63, v63, v78, s[0:1]
	v_mul_f32_e32 v73, 0x37800000, v63
	v_cndmask_b32_e32 v63, v63, v73, vcc
	v_cmp_class_f32_e32 vcc, v62, v64
	s_nop 1
	v_cndmask_b32_e32 v62, v63, v62, vcc
	v_div_scale_f32 v63, s[0:1], v62, v62, 1.0
	v_rcp_f32_e32 v73, v63
	v_div_scale_f32 v78, vcc, 1.0, v62, 1.0
	v_fma_f32 v79, -v63, v73, 1.0
	v_fmac_f32_e32 v73, v79, v73
	v_mul_f32_e32 v79, v78, v73
	v_fma_f32 v80, -v63, v79, v78
	v_fmac_f32_e32 v79, v80, v73
	v_fma_f32 v63, -v63, v79, v78
	v_div_fmas_f32 v63, v63, v73, v79
	v_div_fixup_f32 v62, v63, v62, 1.0
	v_pk_mul_f32 v[30:31], v[30:31], v[62:63] op_sel_hi:[1,0]
	v_pk_mul_f32 v[32:33], v[32:33], v[62:63] op_sel_hi:[1,0]
	v_pk_mul_f32 v[30:31], v[74:75], v[30:31]
	v_pk_mul_f32 v[32:33], v[76:77], v[32:33]
	v_cvt_pk_bf16_f32 v30, v30, v31
	v_cvt_pk_bf16_f32 v31, v32, v33
	global_store_dwordx2 v[60:61], v[30:31], off
	s_nop 1
	v_mov_b32_e32 v30, v132
	v_mov_b32_e32 v31, v133
	v_mov_b32_e32 v32, v134
	v_mov_b32_e32 v33, v135
	v_pk_mul_f32 v[26:27], v[26:27], v[62:63] op_sel_hi:[1,0]
	v_pk_mul_f32 v[28:29], v[28:29], v[62:63] op_sel_hi:[1,0]
	v_pk_mul_f32 v[22:23], v[22:23], v[62:63] op_sel_hi:[1,0]
	v_pk_mul_f32 v[24:25], v[24:25], v[62:63] op_sel_hi:[1,0]
	v_pk_mul_f32 v[18:19], v[18:19], v[62:63] op_sel_hi:[1,0]
	v_pk_mul_f32 v[20:21], v[20:21], v[62:63] op_sel_hi:[1,0]
	v_pk_mul_f32 v[14:15], v[14:15], v[62:63] op_sel_hi:[1,0]
	v_pk_mul_f32 v[16:17], v[16:17], v[62:63] op_sel_hi:[1,0]
	v_pk_mul_f32 v[10:11], v[10:11], v[62:63] op_sel_hi:[1,0]
	v_pk_mul_f32 v[12:13], v[12:13], v[62:63] op_sel_hi:[1,0]
	v_pk_mul_f32 v[6:7], v[6:7], v[62:63] op_sel_hi:[1,0]
	v_pk_mul_f32 v[8:9], v[8:9], v[62:63] op_sel_hi:[1,0]
	v_pk_mul_f32 v[4:5], v[4:5], v[62:63] op_sel_hi:[1,0]
	v_pk_mul_f32 v[2:3], v[2:3], v[62:63] op_sel_hi:[1,0]
	v_mov_b64_e32 v[62:63], v[60:61]
	v_pk_mul_f32 v[28:29], v[32:33], v[28:29]
	v_pk_mul_f32 v[26:27], v[30:31], v[26:27]
	v_cvt_pk_bf16_f32 v26, v26, v27
	v_cvt_pk_bf16_f32 v27, v28, v29
	global_store_dwordx2 v[60:61], v[26:27], off offset:512
	s_nop 1
	v_mov_b32_e32 v26, v136
	v_mov_b32_e32 v27, v137
	v_mov_b32_e32 v28, v138
	v_mov_b32_e32 v29, v139
	v_pk_mul_f32 v[24:25], v[28:29], v[24:25]
	v_pk_mul_f32 v[22:23], v[26:27], v[22:23]
	v_cvt_pk_bf16_f32 v22, v22, v23
	v_cvt_pk_bf16_f32 v23, v24, v25
	global_store_dwordx2 v[60:61], v[22:23], off offset:1024
	s_nop 1
	v_mov_b32_e32 v22, v140
	v_mov_b32_e32 v23, v141
	v_mov_b32_e32 v24, v142
	v_mov_b32_e32 v25, v143
	v_pk_mul_f32 v[20:21], v[24:25], v[20:21]
	v_pk_mul_f32 v[18:19], v[22:23], v[18:19]
	v_cvt_pk_bf16_f32 v18, v18, v19
	v_cvt_pk_bf16_f32 v19, v20, v21
	global_store_dwordx2 v[60:61], v[18:19], off offset:1536
	s_nop 1
	v_mov_b32_e32 v18, v144
	v_mov_b32_e32 v19, v145
	v_mov_b32_e32 v20, v146
	v_mov_b32_e32 v21, v147
	v_pk_mul_f32 v[16:17], v[20:21], v[16:17]
	v_pk_mul_f32 v[14:15], v[18:19], v[14:15]
	v_cvt_pk_bf16_f32 v14, v14, v15
	v_cvt_pk_bf16_f32 v15, v16, v17
	global_store_dwordx2 v[60:61], v[14:15], off offset:2048
	s_nop 1
	v_mov_b32_e32 v14, v148
	v_mov_b32_e32 v15, v149
	v_mov_b32_e32 v16, v150
	v_mov_b32_e32 v17, v151
	v_pk_mul_f32 v[12:13], v[12:13], v[16:17]
	v_pk_mul_f32 v[10:11], v[10:11], v[14:15]
	v_cvt_pk_bf16_f32 v10, v10, v11
	v_cvt_pk_bf16_f32 v11, v12, v13
	global_store_dwordx2 v[60:61], v[10:11], off offset:2560
	s_nop 1
	v_mov_b32_e32 v10, v152
	v_mov_b32_e32 v11, v153
	v_mov_b32_e32 v12, v154
	v_mov_b32_e32 v13, v155
	v_pk_mul_f32 v[8:9], v[8:9], v[12:13]
	v_pk_mul_f32 v[6:7], v[6:7], v[10:11]
	v_cvt_pk_bf16_f32 v6, v6, v7
	v_cvt_pk_bf16_f32 v7, v8, v9
	global_store_dwordx2 v[60:61], v[6:7], off offset:3072
	s_nop 1
	v_mov_b32_e32 v6, v156
	v_mov_b32_e32 v7, v157
	v_mov_b32_e32 v8, v158
	v_mov_b32_e32 v9, v159
	v_pk_mul_f32 v[2:3], v[2:3], v[6:7]
	v_pk_mul_f32 v[4:5], v[4:5], v[8:9]
	s_branch .LBB0_338
